# scan blocks leave the P4 queue loop right after their scan (no trailing queue fetch)
# speedup vs baseline: 1.0050x; 1.0050x over previous
.LBB0_656:
	s_setprio 0
	s_waitcnt lgkmcnt(0)
	s_barrier
	s_cmp_eq_u32 s26, 0x200
	s_cbranch_scc0 .Lp4s_noexit
	s_mov_b64 s[46:47], -1
.Lp4s_noexit:
.LBB0_657:
	s_or_b64 exec, exec, s[0:1]
	s_xor_b64 s[0:1], exec, -1
